# baseline (speedup 1.0000x reference)
; __device__ __forceinline__ unsigned cvt_pk_bf16(float lo, float hi) { unsigned r; asm volatile("v_cvt_pk_bf16_f32 %0, %1, %2" : "=v"(r) : "v"(lo), "v"(hi)); return r; }
; __device__ __forceinline__ void prologue_phase(LAS unsigned char* lds, const Params& p) {
;     ...
; #pragma unroll
;         for (int i = 0; i < 8; ++i) {
;             f32x4 v = *(const f32x4*)(src + 4 * lane + 256 * i);
;             if (!valid) v = (f32x4){0.f, 0.f, 0.f, 0.f};
;             ss += v[0] * v[0] + v[1] * v[1] + v[2] * v[2] + v[3] * v[3];
;             u32x2 o; o.x = cvt_pk_bf16(v[0], v[1]); o.y = cvt_pk_bf16(v[2], v[3]);
;             *(u32x2*)(HB + (size_t)r * 2048 + 4 * lane + 256 * i) = o;
;         }
; #pragma unroll
;         for (int o = 32; o > 0; o >>= 1) ss += __shfl_xor(ss, o);
;         if (lane == 0) { SS[r] = (unsigned long long)(ss * 16777216.f); SS[MROWS + r] = 0ull; SS[2 * MROWS + r] = 0ull; SS[3 * MROWS + r] = 0ull; SS[4 * MROWS + r] = 0ull; }
.LBB0_44:
	s_or_b64 exec, exec, s[6:7]
	s_waitcnt lgkmcnt(0)
	v_lshl_add_u64 v[10:11], v[10:11], 0, v[8:9]
	v_add_co_u32_e64 v84, s[6:7], s50, v10
	s_nop 1
	v_addc_co_u32_e64 v85, s[6:7], 0, v11, s[6:7]
	global_load_dwordx4 v[52:55], v[10:11], off
	global_load_dwordx4 v[56:59], v[10:11], off offset:1024
	global_load_dwordx4 v[60:63], v[10:11], off offset:2048
	global_load_dwordx4 v[64:67], v[10:11], off offset:3072
	global_load_dwordx4 v[68:71], v[84:85], off
	global_load_dwordx4 v[72:75], v[84:85], off offset:1024
	global_load_dwordx4 v[76:79], v[84:85], off offset:2048
	global_load_dwordx4 v[80:83], v[84:85], off offset:3072
	v_lshlrev_b64 v[24:25], 12, v[2:3]
	v_lshl_add_u64 v[24:25], v[6:7], 0, v[24:25]
	v_cmp_gt_i32_e32 vcc, s49, v2
	v_cmp_lt_i32_e64 s[6:7], v13, v12
	s_waitcnt vmcnt(7)
	v_cndmask_b32_e32 v4, 0, v55, vcc
	v_cndmask_b32_e32 v19, 0, v54, vcc
	v_cndmask_b32_e32 v26, 0, v52, vcc
	v_cndmask_b32_e32 v27, 0, v53, vcc
	v_cvt_pk_bf16_f32 v20, v26, v27
	v_cvt_pk_bf16_f32 v21, v19, v4
	global_store_dwordx2 v[24:25], v[20:21], off
	s_waitcnt vmcnt(7)
	v_cndmask_b32_e32 v28, 0, v59, vcc
	v_cndmask_b32_e32 v29, 0, v58, vcc
	v_cndmask_b32_e32 v30, 0, v56, vcc
	v_cndmask_b32_e32 v31, 0, v57, vcc
	v_cvt_pk_bf16_f32 v20, v30, v31
	v_cvt_pk_bf16_f32 v21, v29, v28
	global_store_dwordx2 v[24:25], v[20:21], off offset:512
	s_waitcnt vmcnt(7)
	v_cndmask_b32_e32 v32, 0, v63, vcc
	v_cndmask_b32_e32 v33, 0, v62, vcc
	v_cndmask_b32_e32 v34, 0, v60, vcc
	v_cndmask_b32_e32 v35, 0, v61, vcc
	v_cvt_pk_bf16_f32 v20, v34, v35
	v_cvt_pk_bf16_f32 v21, v33, v32
	global_store_dwordx2 v[24:25], v[20:21], off offset:1024
	s_waitcnt vmcnt(7)
	v_cndmask_b32_e32 v36, 0, v67, vcc
	v_cndmask_b32_e32 v37, 0, v66, vcc
	v_cndmask_b32_e32 v38, 0, v64, vcc
	v_cndmask_b32_e32 v39, 0, v65, vcc
	v_cvt_pk_bf16_f32 v20, v38, v39
	v_cvt_pk_bf16_f32 v21, v37, v36
	global_store_dwordx2 v[24:25], v[20:21], off offset:1536
	s_waitcnt vmcnt(7)
	v_cndmask_b32_e32 v40, 0, v71, vcc
	v_cndmask_b32_e32 v41, 0, v70, vcc
	v_cndmask_b32_e32 v42, 0, v68, vcc
	v_cndmask_b32_e32 v43, 0, v69, vcc
	v_cvt_pk_bf16_f32 v20, v42, v43
	v_cvt_pk_bf16_f32 v21, v41, v40
	global_store_dwordx2 v[24:25], v[20:21], off offset:2048
	s_waitcnt vmcnt(7)
	v_cndmask_b32_e32 v44, 0, v75, vcc
	v_cndmask_b32_e32 v45, 0, v74, vcc
	v_cndmask_b32_e32 v46, 0, v72, vcc
	v_cndmask_b32_e32 v47, 0, v73, vcc
	v_cvt_pk_bf16_f32 v20, v46, v47
	v_cvt_pk_bf16_f32 v21, v45, v44
	global_store_dwordx2 v[24:25], v[20:21], off offset:2560
	s_waitcnt vmcnt(7)
	v_cndmask_b32_e32 v48, 0, v79, vcc
	v_cndmask_b32_e32 v49, 0, v78, vcc
	v_cndmask_b32_e32 v50, 0, v76, vcc
	v_cndmask_b32_e32 v51, 0, v77, vcc
	v_cvt_pk_bf16_f32 v20, v50, v51
	v_cvt_pk_bf16_f32 v21, v49, v48
	global_store_dwordx2 v[24:25], v[20:21], off offset:3072
	v_mul_f32_e32 v11, v27, v27
	v_fmac_f32_e32 v11, v26, v26
	v_fmac_f32_e32 v11, v19, v19
	v_fmac_f32_e32 v11, v4, v4
	v_mul_f32_e32 v4, v31, v31
	v_fmac_f32_e32 v4, v30, v30
	v_fmac_f32_e32 v4, v29, v29
	v_fmac_f32_e32 v4, v28, v28
	v_add_f32_e32 v4, v11, v4
	v_mul_f32_e32 v11, v35, v35
	v_fmac_f32_e32 v11, v34, v34
	v_fmac_f32_e32 v11, v33, v33
	v_fmac_f32_e32 v11, v32, v32
	v_add_f32_e32 v4, v4, v11
	v_mul_f32_e32 v11, v39, v39
	v_fmac_f32_e32 v11, v38, v38
	v_fmac_f32_e32 v11, v37, v37
	v_fmac_f32_e32 v11, v36, v36
	v_add_f32_e32 v4, v4, v11
	v_mul_f32_e32 v11, v43, v43
	v_fmac_f32_e32 v11, v42, v42
	v_fmac_f32_e32 v11, v41, v41
	v_fmac_f32_e32 v11, v40, v40
	v_add_f32_e32 v4, v4, v11
	v_mul_f32_e32 v11, v47, v47
	v_fmac_f32_e32 v11, v46, v46
	v_fmac_f32_e32 v11, v45, v45
	v_fmac_f32_e32 v11, v44, v44
	v_add_f32_e32 v4, v4, v11
	v_mul_f32_e32 v11, v51, v51
	v_fmac_f32_e32 v11, v50, v50
	v_fmac_f32_e32 v11, v49, v49
	v_fmac_f32_e32 v11, v48, v48
	v_add_f32_e32 v4, v4, v11
	v_cndmask_b32_e64 v10, v1, v13, s[6:7]
	v_lshlrev_b32_e32 v10, 2, v10
	s_waitcnt vmcnt(7)
	v_cndmask_b32_e32 v21, 0, v81, vcc
	v_cndmask_b32_e32 v19, 0, v82, vcc
	v_cndmask_b32_e32 v20, 0, v80, vcc
	v_mul_f32_e32 v22, v21, v21
	v_fmac_f32_e32 v22, v20, v20
	v_cndmask_b32_e32 v11, 0, v83, vcc
	v_fmac_f32_e32 v22, v19, v19
	v_fmac_f32_e32 v22, v11, v11
	v_add_f32_e32 v4, v4, v22
	ds_bpermute_b32 v10, v10, v4
	v_cmp_lt_i32_e32 vcc, v14, v12
	v_cvt_pk_bf16_f32 v20, v20, v21
	v_cvt_pk_bf16_f32 v21, v19, v11
	global_store_dwordx2 v[24:25], v[20:21], off offset:3584
	s_waitcnt lgkmcnt(0)
	v_add_f32_e32 v4, v4, v10
	v_cndmask_b32_e32 v22, v1, v14, vcc
	v_lshlrev_b32_e32 v22, 2, v22
	ds_bpermute_b32 v10, v22, v4
	v_cmp_lt_i32_e32 vcc, v15, v12
	s_waitcnt lgkmcnt(0)
	v_add_f32_e32 v4, v4, v10
	v_cndmask_b32_e32 v22, v1, v15, vcc
	v_lshlrev_b32_e32 v22, 2, v22
	ds_bpermute_b32 v10, v22, v4
	v_cmp_lt_i32_e32 vcc, v16, v12
	s_waitcnt lgkmcnt(0)
	v_add_f32_e32 v4, v4, v10
	v_cndmask_b32_e32 v22, v1, v16, vcc
	v_lshlrev_b32_e32 v22, 2, v22
	ds_bpermute_b32 v10, v22, v4
	v_cmp_lt_i32_e32 vcc, v17, v12
	s_waitcnt lgkmcnt(0)
	v_add_f32_e32 v4, v4, v10
	v_cndmask_b32_e32 v22, v1, v17, vcc
	v_lshlrev_b32_e32 v22, 2, v22
	ds_bpermute_b32 v10, v22, v4
	v_cmp_lt_i32_e32 vcc, v18, v12
	s_waitcnt lgkmcnt(0)
	v_add_f32_e32 v4, v4, v10
	v_cndmask_b32_e32 v22, v1, v18, vcc
	v_lshlrev_b32_e32 v10, 2, v22
	ds_bpermute_b32 v10, v10, v4
	s_and_saveexec_b64 s[6:7], s[4:5]
	s_cbranch_execz .LBB0_35
	s_waitcnt lgkmcnt(0)
	v_add_f32_e32 v4, v4, v10
	v_mul_f32_e32 v4, 0x4b800000, v4
	v_trunc_f32_e32 v4, v4
	v_mul_f32_e32 v10, 0x2f800000, v4
	v_floor_f32_e32 v10, v10
	v_fmac_f32_e32 v4, 0xcf800000, v10
	v_cvt_u32_f32_e32 v11, v10
	v_cvt_u32_f32_e32 v10, v4
	v_lshl_add_u64 v[20:21], v[2:3], 3, s[80:81]
	s_mov_b32 s11, s10
	v_mov_b64_e32 v[22:23], s[10:11]
	global_store_dwordx2 v[20:21], v[10:11], off
	v_add_co_u32_e32 v10, vcc, 0x30000, v20
	s_nop 1
	v_addc_co_u32_e32 v11, vcc, 0, v21, vcc
	global_store_dwordx2 v[10:11], v[22:23], off offset:2048
	v_add_co_u32_e32 v10, vcc, 0x61000, v20
	s_nop 1
	v_addc_co_u32_e32 v11, vcc, 0, v21, vcc
	global_store_dwordx2 v[10:11], v[22:23], off
	v_add_co_u32_e32 v10, vcc, 0x91000, v20
	s_nop 1
	v_addc_co_u32_e32 v11, vcc, 0, v21, vcc
	global_store_dwordx2 v[10:11], v[22:23], off offset:2048
	v_add_co_u32_e32 v10, vcc, 0xc2000, v20
	s_nop 1
	v_addc_co_u32_e32 v11, vcc, 0, v21, vcc
	global_store_dwordx2 v[10:11], v[22:23], off
	s_branch .LBB0_35
